# static s_setprio 1 for waves 4-7 during the mixer phase (attention/cross/pool)
# baseline (speedup 1.0000x reference)
.LBB0_873:
	s_andn2_b64 vcc, exec, s[0:1]
	s_cbranch_vccnz .LBB0_939
	v_readfirstlane_b32 s0, v250
	s_nop 3
	s_lshr_b32 s0, s0, 8
	s_cmp_lg_u32 s0, 0
	s_cbranch_scc0 .Lprio_skip
	s_setprio 1
.Lprio_skip:
	v_mov_b32_e32 v0, v250
	v_readlane_b32 s0, v255, 0
	s_lshl_b32 s0, s0, 6
	v_readlane_b32 s1, v255, 1
	v_and_or_b32 v0, v0, 63, s0
	v_ashrrev_i32_e32 v1, 31, v0
	v_lshlrev_b64 v[0:1], 2, v[0:1]
	v_lshl_add_u64 v[2:3], s[58:59], 0, v[0:1]
	v_lshl_add_u64 v[0:1], s[60:61], 0, v[0:1]
	global_load_dword v2, v[2:3], off
	v_readlane_b32 s0, v253, 13
	global_load_dword v4, v[0:1], off
	v_readlane_b32 s1, v253, 14
	s_andn2_b64 vcc, exec, s[0:1]
	s_waitcnt vmcnt(0)
	v_and_b32_e32 v3, 0x7fffffff, v2
	s_nop 1
	v_mov_b32_dpp v0, v3 quad_perm:[1,0,3,2] row_mask:0xf bank_mask:0xf bound_ctrl:1
	v_and_b32_e32 v5, 0x7fffffff, v4
	v_max_f32_e64 v1, |v2|, |v2|
	v_max_f32_e32 v0, v0, v0
	v_mov_b32_dpp v2, v5 quad_perm:[1,0,3,2] row_mask:0xf bank_mask:0xf bound_ctrl:1
	v_max_f32_e64 v3, |v4|, |v4|
	v_max_f32_e32 v2, v2, v2
	v_max_f32_e32 v0, v1, v0
	v_max_f32_e32 v2, v3, v2
	s_nop 0
	v_mov_b32_dpp v1, v0 quad_perm:[2,3,0,1] row_mask:0xf bank_mask:0xf bound_ctrl:1
	v_mov_b32_dpp v3, v2 quad_perm:[2,3,0,1] row_mask:0xf bank_mask:0xf bound_ctrl:1
	v_max_f32_e32 v1, v1, v1
	v_max_f32_e32 v3, v3, v3
	v_max_f32_e32 v0, v0, v1
	v_max_f32_e32 v2, v2, v3
	s_nop 0
	v_mov_b32_dpp v1, v0 row_half_mirror row_mask:0xf bank_mask:0xf bound_ctrl:1
	v_mov_b32_dpp v3, v2 row_half_mirror row_mask:0xf bank_mask:0xf bound_ctrl:1
	v_max_f32_e32 v1, v1, v1
	v_max_f32_e32 v3, v3, v3
	v_max_f32_e32 v0, v0, v1
	v_max_f32_e32 v2, v2, v3
	s_nop 0
	v_mov_b32_dpp v1, v0 row_mirror row_mask:0xf bank_mask:0xf bound_ctrl:1
	v_mov_b32_dpp v3, v2 row_mirror row_mask:0xf bank_mask:0xf bound_ctrl:1
	v_max_f32_e32 v1, v1, v1
	v_max_f32_e32 v3, v3, v3
	v_max_f32_e32 v0, v0, v1
	v_max_f32_e32 v2, v2, v3
	v_mov_b32_e32 v1, v0
	v_mov_b32_e32 v3, v2
	s_nop 0
	v_permlane16_swap_b32_e32 v0, v1
	v_permlane16_swap_b32_e32 v2, v3
	v_max_f32_e32 v1, v1, v1
	v_max_f32_e32 v0, v0, v0
	v_max_f32_e32 v3, v3, v3
	v_max_f32_e32 v2, v2, v2
	v_max_f32_e32 v0, v0, v1
	v_max_f32_e32 v2, v2, v3
	v_mov_b32_e32 v1, v0
	v_mov_b32_e32 v3, v2
	s_nop 0
	v_permlane32_swap_b32_e32 v0, v1
	v_permlane32_swap_b32_e32 v2, v3
	s_cbranch_vccnz .LBB0_900
	v_mov_b32_e32 v8, v250
	v_readlane_b32 s0, v254, 38
	v_readlane_b32 s1, v254, 39
	v_ashrrev_i32_e32 v4, 1, v8
	v_bfi_b32 v6, s88, v4, v8
	v_mov_b64_e32 v[4:5], s[0:1]
	v_mad_i64_i32 v[4:5], s[0:1], v6, s33, v[4:5]
	v_lshrrev_b32_e32 v6, 1, v8
	v_and_b32_e32 v176, 16, v6
	v_readlane_b32 s0, v254, 40
	v_lshl_add_u64 v[4:5], v[4:5], 0, v[176:177]
	v_readlane_b32 s1, v254, 41
	global_load_dwordx4 v[96:99], v[4:5], off offset:1024
	global_load_dwordx4 v[100:103], v[4:5], off offset:1056
	global_load_dwordx4 v[104:107], v[4:5], off offset:1088
	global_load_dwordx4 v[108:111], v[4:5], off offset:1120
	v_ashrrev_i32_e32 v4, 3, v8
	v_mov_b64_e32 v[6:7], s[0:1]
	v_lshlrev_b32_e32 v8, 4, v8
	v_mad_i64_i32 v[6:7], s[0:1], v4, s33, v[6:7]
	v_and_b32_e32 v176, 0x70, v8
	v_lshl_add_u64 v[6:7], v[6:7], 0, v[176:177]
	s_mov_b32 s0, 0x48000
	v_ashrrev_i32_e32 v5, 31, v4
	v_add_co_u32_e32 v8, vcc, s0, v6
	v_readlane_b32 s0, v253, 15
	s_nop 0
	v_addc_co_u32_e32 v9, vcc, 0, v7, vcc
	v_lshlrev_b64 v[4:5], s0, v[4:5]
	v_readlane_b32 s0, v254, 42
	global_load_dwordx4 v[64:67], v[6:7], off offset:2048
	global_load_dwordx4 v[68:71], v[8:9], off offset:2048
	v_add_co_u32_e32 v6, vcc, 0x90000, v6
	v_readlane_b32 s1, v254, 43
	s_nop 0
	v_addc_co_u32_e32 v7, vcc, 0, v7, vcc
	v_lshl_add_u64 v[4:5], v[4:5], 1, s[0:1]
	v_lshl_add_u64 v[4:5], v[4:5], 0, v[176:177]
	global_load_dwordx4 v[72:75], v[6:7], off offset:2048
	global_load_dwordx4 v[76:79], v[4:5], off
	v_max_f32_e32 v0, v0, v0
	v_max_f32_e32 v1, v1, v1
	v_max_f32_e32 v0, v0, v1
	v_max_f32_e32 v1, v2, v2
	v_max_f32_e32 v2, v3, v3
	v_max_f32_e32 v1, v1, v2
	v_mul_f32_e32 v0, 0x41000000, v0
	v_mul_f32_e32 v0, v0, v1
	v_mul_f32_e32 v0, 0x3f828f5c, v0
	v_mul_f32_e32 v0, 0x3fb8aa3b, v0
	s_mov_b32 s0, 0x41e00000
	v_cmp_ngt_f32_e64 s[36:37], s0, v0
	s_mov_b32 s8, s46
	s_waitcnt vmcnt(0)
	s_branch .LBB0_877
